# v39 + scan C loop: 4 v_xor sign flips folded into v_cvt_pk_f16_f32 neg modifiers (serial chain)
# baseline (speedup 1.0000x reference)
.LBB0_580:
	ds_read2_b64 v[178:181], v42 offset1:4
	ds_read_b128 v[182:185], v82
	ds_read_b128 v[186:189], v82 offset:64
	ds_read2_b64 v[190:193], v42 offset0:8 offset1:12
	ds_read_b64_tr_b16 v[30:31], v83
	v_add_u32_e32 v83, 0x3700, v83
	ds_read2st64_b64 v[194:197], v85 offset1:1
	ds_read_b128 v[198:201], v43
	ds_read_b128 v[202:205], v82 offset:128
	ds_read_b64_tr_b16 v[158:159], v84 offset:6912
	ds_read_b64_tr_b16 v[162:163], v84 offset:6944
	ds_read_b64_tr_b16 v[166:167], v84 offset:6976
	s_waitcnt lgkmcnt(12)
	ds_read_b64_tr_b16 v[170:171], v84 offset:7008
	s_waitcnt lgkmcnt(12)
	ds_read_b64_tr_b16 v[38:39], v84 offset:4608
	s_waitcnt lgkmcnt(5)
	v_pk_mul_f32 v[16:17], v[16:17], v[202:203]
	v_add_u32_e32 v202, 0x800, v42
	v_add_u32_e32 v42, 0x3700, v42
	v_pk_mul_f32 v[18:19], v[18:19], v[204:205]
	v_pk_mul_f32 v[14:15], v[14:15], v[188:189]
	v_cvt_pk_f16_f32 v189, v18, v19
	v_cvt_pk_f16_f32 v188, v16, v17
	v_pk_mul_f32 v[6:7], v[6:7], v[184:185]
	v_pk_mul_f32 v[4:5], v[4:5], v[182:183]
	ds_read2st64_b64 v[182:185], v85 offset0:2 offset1:3
	v_add_u32_e32 v85, 0x3700, v85
	s_waitcnt lgkmcnt(2)
	v_mfma_f32_16x16x16_f16 v[170:173], v[170:171], v[30:31], v[16:19]
	v_pk_mul_f32 v[12:13], v[12:13], v[186:187]
	v_mfma_f32_16x16x16_f16 v[16:19], v[194:195], v[30:31], 0
	v_mul_f32_e64 v2, v2, v200
	v_mul_f32_e64 v3, v3, v201
	v_pk_mul_f32 v[0:1], v[0:1], v[198:199]
	v_cvt_pk_f16_f32 v187, v14, v15
	v_cvt_pk_f16_f32 v186, v12, v13
	v_cvt_pk_f16_f32 v201, v6, v7
	v_cvt_pk_f16_f32 v199, v2, v3
	v_cvt_pk_f16_f32 v200, v4, v5
	v_cvt_pk_f16_f32 v198, v0, v1
	v_mfma_f32_16x16x32_f16 v[190:193], v[190:193], v[186:189], 0
	v_mfma_f32_16x16x16_f16 v[162:165], v[162:163], v[30:31], v[4:7]
	v_mfma_f32_16x16x32_f16 v[4:7], v[178:181], v[198:201], v[16:19]
	v_mfma_f32_16x16x16_f16 v[12:15], v[166:167], v[30:31], v[12:15]
	ds_read_b64_tr_b16 v[174:175], v84 offset:4640
	ds_read2_b64 v[166:169], v202 offset0:40 offset1:44
	ds_read_b64_tr_b16 v[22:23], v84 offset:4672
	s_nop 3
	v_pk_add_f32 v[6:7], v[6:7], v[192:193]
	v_pk_add_f32 v[4:5], v[4:5], v[190:191]
	v_cvt_pk_f16_f32 v35, v6, v7
	v_cvt_pk_f16_f32 v34, v4, v5
	s_waitcnt lgkmcnt(3)
	s_nop 0
	v_mfma_f32_16x16x16_f16 v[4:7], v[184:185], v[34:35], 0
	v_mfma_f32_16x16x16_f16 v[158:161], v[158:159], v[30:31], v[0:3]
	s_nop 6
	s_waitcnt lgkmcnt(1)
	v_mfma_f32_16x16x32_f16 v[0:3], v[166:169], v[186:189], 0
	v_cvt_pk_f16_f32 v19, -v6, -v7
	v_cvt_pk_f16_f32 v18, -v4, -v5
	v_mfma_f32_16x16x16_f16 v[6:9], v[196:197], v[30:31], 0
	s_add_i32 s24, s24, -1
	v_mfma_f32_16x16x16_f16 v[30:33], v[38:39], v[18:19], v[158:161]
	ds_read_b64_tr_b16 v[26:27], v84 offset:4704
	v_add_u32_e32 v84, 0x3700, v84
	ds_read_b128 v[38:41], v43 offset:256
	v_add_u32_e32 v43, 0x3700, v43
	s_nop 0
	ds_read_b128 v[158:161], v82 offset:256
	v_mfma_f32_16x16x16_f16 v[34:37], v[174:175], v[18:19], v[162:165]
	s_waitcnt lgkmcnt(3)
	v_mfma_f32_16x16x16_f16 v[12:15], v[22:23], v[18:19], v[12:15]
	ds_read_b128 v[22:25], v82 offset:320
	ds_read_b128 v[162:165], v82 offset:384
	v_add_u32_e32 v82, 0x3700, v82
	v_mfma_f32_16x16x16_f16 v[166:169], v[182:183], v[18:19], v[0:3]
	s_waitcnt lgkmcnt(2)
	v_pk_mul_f32 v[4:5], v[158:159], v[34:35]
	ds_read2_b64 v[0:3], v202 offset0:32 offset1:36
	v_mfma_f32_16x16x16_f16 v[26:29], v[26:27], v[18:19], v[170:173]
	s_waitcnt lgkmcnt(2)
	v_pk_mul_f32 v[14:15], v[24:25], v[14:15]
	v_pk_mul_f32 v[12:13], v[22:23], v[12:13]
	s_waitcnt lgkmcnt(0)
	v_mfma_f32_16x16x32_f16 v[170:173], v[0:3], v[198:201], v[6:9]
	v_mul_f32_e64 v2, v40, v32
	v_mul_f32_e64 v3, v41, v33
	v_pk_mul_f32 v[0:1], v[38:39], v[30:31]
	v_pk_mul_f32 v[6:7], v[160:161], v[36:37]
	v_pk_mul_f32 v[18:19], v[164:165], v[28:29]
	v_pk_mul_f32 v[16:17], v[162:163], v[26:27]
	s_nop 1
	v_pk_add_f32 v[20:21], v[170:171], v[166:167]
	v_pk_add_f32 v[8:9], v[172:173], v[168:169]
	ds_write2st64_b32 v86, v20, v21 offset1:1
	ds_write2st64_b32 v86, v8, v9 offset0:2 offset1:3
	v_add_u32_e32 v86, 0x1000, v86
	s_cmp_lg_u32 s24, 0
	s_cbranch_scc1 .LBB0_580
